# FFN norm (f16 rows): next row's data prefetched one iteration ahead into v72-v79, counted waits, head waits skipped for the pipelined path (on keep_v8)
# speedup vs baseline: 1.0073x; 1.0073x over previous
.LBB0_775:
	s_xor_b64 s[72:73], s[18:19], -1
	s_cmp_lg_u32 s65, 3
	s_cselect_b64 s[16:17], -1, 0
	s_cmp_eq_u32 s65, 3
	s_cselect_b64 s[94:95], -1, 0
	s_and_b64 s[26:27], s[94:95], exec
	s_mov_b32 s20, 0x9000
	s_cselect_b32 s20, 0x8000, s20
	s_ashr_i32 s24, s24, 6
	v_readlane_b32 s25, v255, 1
	s_add_i32 s24, s24, s25
	s_cmp_ge_i32 s24, s20
	s_cbranch_scc1 .LBB0_784
	v_readlane_b32 s26, v255, 57
	s_add_u32 s36, s6, 0x19000000
	v_readlane_b32 s27, v255, 58
	s_addc_u32 s37, s7, 0
	s_lshl_b64 s[26:27], s[26:27], 2
	s_add_u32 s25, s6, s26
	s_addc_u32 s29, s7, s27
	s_cmp_lt_u32 s9, 2
	s_cselect_b64 s[6:7], -1, 0
	s_and_b64 s[26:27], s[6:7], exec
	v_readlane_b32 s28, v255, 56
	s_cselect_b32 s9, s37, 0
	s_cselect_b32 s26, s36, 0
	s_lshl_b32 s27, s28, 13
	v_lshlrev_b32_e32 v18, 2, v0
	s_waitcnt lgkmcnt(0)
	s_add_u32 s2, s2, s27
	v_and_b32_e32 v34, 0xfc, v18
	s_addc_u32 s3, s3, 0
	v_lshlrev_b32_e32 v14, 2, v34
	global_load_dwordx4 v[2:5], v14, s[2:3]
	global_load_dwordx4 v[6:9], v14, s[2:3] offset:1024
	global_load_dwordx4 v[10:13], v14, s[2:3] offset:2048
	s_nop 0
	global_load_dwordx4 v[14:17], v14, s[2:3] offset:3072
	s_mul_i32 s2, s28, 0x6000
	s_add_u32 s28, s25, s2
	s_addc_u32 s29, s29, 0
	s_add_u32 s38, s26, 0x800000
	s_addc_u32 s39, s9, 0
	s_add_u32 s60, s26, 0x1000000
	s_addc_u32 s61, s9, 0
	s_add_u32 s74, s26, 0x1800000
	s_addc_u32 s75, s9, 0
	s_movk_i32 s2, 0x80
	s_ashr_i32 s25, s24, 31
	v_bitop3_b32 v52, v18, s2, v246 bitop3:0x6c
	s_lshl_b64 s[2:3], s[24:25], 11
	v_and_b32_e32 v0, 63, v0
	s_add_u32 s2, s4, s2
	v_bitop3_b32 v35, v18, 4, v246 bitop3:0x6c
	v_bitop3_b32 v48, v18, 8, v246 bitop3:0x6c
	v_bitop3_b32 v49, v18, 16, v246 bitop3:0x6c
	v_bitop3_b32 v50, v18, 32, v246 bitop3:0x6c
	v_bitop3_b32 v51, v18, 64, v246 bitop3:0x6c
	v_or_b32_e32 v18, 0x100, v34
	v_or_b32_e32 v20, 0x200, v34
	v_or_b32_e32 v22, 0x300, v34
	v_lshlrev_b32_e32 v0, 3, v0
	s_addc_u32 s3, s5, s3
	v_lshl_add_u64 v[36:37], s[2:3], 0, v[0:1]
	v_lshlrev_b32_e32 v53, 2, v18
	v_lshlrev_b32_e32 v54, 2, v20
	v_lshlrev_b32_e32 v55, 2, v22
	s_and_b64 vcc, exec, s[72:73]
	s_cbranch_vccz .Lnf_pro_done
	s_mov_b32 s98, s24
	s_add_i32 s99, s98, 0xffff8000
	s_cmpk_gt_i32 s98, 0x7fff
	s_cselect_b32 s98, s99, s98
	s_cselect_b32 s101, s23, s13
	s_cselect_b32 s100, s22, s12
	s_ashr_i32 s99, s98, 31
	s_lshl_b64 s[98:99], s[98:99], 10
	v_mov_b32_e32 v81, s99
	v_or_b32_e32 v80, s98, v34
	v_lshl_add_u64 v[80:81], v[80:81], 1, s[100:101]
	global_load_dwordx2 v[72:73], v[80:81], off
	global_load_dwordx2 v[74:75], v[80:81], off offset:512
	global_load_dwordx2 v[76:77], v[80:81], off offset:1024
	global_load_dwordx2 v[78:79], v[80:81], off offset:1536
	global_load_dword v82, v[80:81], off
	global_load_dword v82, v[80:81], off
	global_load_dword v82, v[80:81], off
	global_load_dword v82, v[80:81], off
.Lnf_pro_done:
	s_branch .LBB0_778
.LBB0_777:
	s_waitcnt vmcnt(3)
	v_pk_mul_f32 v[42:43], v[32:33], v[32:33]
	v_pk_mul_f32 v[44:45], v[30:31], v[30:31]
	s_waitcnt vmcnt(2)
	v_pk_mul_f32 v[38:39], v[28:29], v[28:29]
	v_pk_mul_f32 v[40:41], v[26:27], v[26:27]
	v_pk_mov_b32 v[46:47], v[44:45], v[42:43] op_sel:[1,0]
	v_mov_b32_e32 v45, v43
	v_pk_add_f32 v[42:43], v[46:47], v[44:45]
	v_pk_mov_b32 v[44:45], v[40:41], v[38:39] op_sel:[1,0]
	v_mov_b32_e32 v41, v39
	s_waitcnt vmcnt(1)
	v_mul_f32_e32 v0, v22, v22
	v_pk_add_f32 v[38:39], v[44:45], v[40:41]
	v_pk_fma_f32 v[40:41], v[22:23], v[22:23], v[0:1] op_sel_hi:[1,1,0]
	v_mul_f32_e32 v0, v24, v24
	v_pk_add_f32 v[42:43], v[42:43], v[42:43] op_sel_hi:[0,1]
	v_pk_add_f32 v[38:39], v[38:39], v[38:39] op_sel_hi:[0,1]
	v_pk_fma_f32 v[44:45], v[24:25], v[24:25], v[0:1] op_sel_hi:[1,1,0]
	s_waitcnt vmcnt(0)
.Lnf_join:
	s_waitcnt vmcnt(4)
	v_mul_f32_e32 v40, v18, v18
	v_mul_f32_e32 v44, v19, v19
	v_mul_f32_e32 v42, v20, v20
	v_mul_f32_e32 v38, v21, v21
	v_pk_add_f32 v[40:41], v[40:41], v[44:45]
	v_pk_add_f32 v[38:39], v[42:43], v[38:39]
	s_min_i32 s2, s24, 0x8000
	v_pk_add_f32 v[38:39], v[40:41], v[38:39]
	s_ashr_i32 s2, s2, 11
	v_add_f32_e32 v0, v38, v39
	ds_bpermute_b32 v38, v35, v0
	s_mul_hi_i32 s3, s2, 0x9000
	s_mul_i32 s2, s2, 0x9000
	s_add_u32 s4, s28, s2
	s_addc_u32 s5, s29, s3
	s_waitcnt lgkmcnt(0)
	v_add_f32_e32 v0, v0, v38
	ds_bpermute_b32 v38, v48, v0
	s_add_u32 s96, s4, 0x1000
	s_addc_u32 s97, s5, 0
	v_lshlrev_b32_e32 v46, 2, v34
	s_add_i32 s24, s24, s10
	s_waitcnt lgkmcnt(0)
	v_add_f32_e32 v0, v0, v38
	ds_bpermute_b32 v38, v49, v0
	s_cmp_lt_i32 s24, s20
	s_waitcnt lgkmcnt(0)
	v_add_f32_e32 v0, v0, v38
	ds_bpermute_b32 v38, v50, v0
	s_waitcnt lgkmcnt(0)
	v_add_f32_e32 v0, v0, v38
	ds_bpermute_b32 v38, v51, v0
	s_waitcnt lgkmcnt(0)
	v_add_f32_e32 v0, v0, v38
	ds_bpermute_b32 v38, v52, v0
	s_waitcnt lgkmcnt(0)
	v_add_f32_e32 v0, v0, v38
	v_fmamk_f32 v0, v0, 0x3a800000, v240
	v_cmp_gt_f32_e32 vcc, s77, v0
	v_mul_f32_e32 v38, 0x4f800000, v0
	s_nop 0
	v_cndmask_b32_e32 v0, v0, v38, vcc
	v_sqrt_f32_e32 v38, v0
	s_nop 0
	v_add_u32_e32 v39, -1, v38
	v_fma_f32 v40, -v39, v38, v0
	v_cmp_ge_f32_e64 s[2:3], 0, v40
	v_add_u32_e32 v40, 1, v38
	s_nop 0
	v_cndmask_b32_e64 v39, v38, v39, s[2:3]
	v_fma_f32 v38, -v40, v38, v0
	v_cmp_lt_f32_e64 s[2:3], 0, v38
	s_nop 1
	v_cndmask_b32_e64 v38, v39, v40, s[2:3]
	v_mul_f32_e32 v39, 0x37800000, v38
	v_cndmask_b32_e32 v38, v38, v39, vcc
	v_cmp_class_f32_e32 vcc, v0, v241
	s_nop 1
	v_cndmask_b32_e32 v0, v38, v0, vcc
	v_div_scale_f32 v38, s[2:3], v0, v0, 1.0
	v_rcp_f32_e32 v39, v38
	s_nop 0
	v_fma_f32 v40, -v38, v39, 1.0
	v_fmac_f32_e32 v39, v40, v39
	v_div_scale_f32 v40, vcc, 1.0, v0, 1.0
	v_mul_f32_e32 v41, v40, v39
	v_fma_f32 v42, -v38, v41, v40
	v_fmac_f32_e32 v41, v42, v39
	v_fma_f32 v38, -v38, v41, v40
	v_div_fmas_f32 v38, v38, v39, v41
	v_div_fixup_f32 v0, v38, v0, 1.0
	v_pk_mul_f32 v[32:33], v[32:33], v[0:1] op_sel_hi:[1,0]
	v_pk_mul_f32 v[30:31], v[30:31], v[0:1] op_sel_hi:[1,0]
	v_pk_mul_f32 v[32:33], v[4:5], v[32:33]
	v_pk_mul_f32 v[30:31], v[2:3], v[30:31]
	v_pk_mul_f32 v[28:29], v[28:29], v[0:1] op_sel_hi:[1,0]
	v_pk_mul_f32 v[26:27], v[26:27], v[0:1] op_sel_hi:[1,0]
	v_pk_mul_f32 v[28:29], v[8:9], v[28:29]
	v_pk_mul_f32 v[26:27], v[6:7], v[26:27]
	v_pk_mul_f32 v[24:25], v[24:25], v[0:1] op_sel_hi:[1,0]
	v_pk_mul_f32 v[22:23], v[22:23], v[0:1] op_sel_hi:[1,0]
	v_pk_mul_f32 v[24:25], v[12:13], v[24:25]
	v_pk_mul_f32 v[22:23], v[10:11], v[22:23]
	v_pk_mul_f32 v[20:21], v[20:21], v[0:1] op_sel_hi:[1,0]
	v_pk_mul_f32 v[18:19], v[18:19], v[0:1] op_sel_hi:[1,0]
	v_pk_mul_f32 v[20:21], v[16:17], v[20:21]
	v_pk_mul_f32 v[18:19], v[14:15], v[18:19]
	v_pk_add_f32 v[118:119], v[118:119], 1.0 op_sel_hi:[1,0]
	v_pk_add_f32 v[116:117], v[116:117], 1.0 op_sel_hi:[1,0]
	v_pk_add_f32 v[122:123], v[122:123], 1.0 op_sel_hi:[1,0]
	v_pk_add_f32 v[120:121], v[120:121], 1.0 op_sel_hi:[1,0]
	v_pk_fma_f32 v[32:33], v[118:119], v[32:33], v[102:103]
	v_pk_fma_f32 v[30:31], v[116:117], v[30:31], v[100:101]
	v_pk_add_f32 v[126:127], v[126:127], 1.0 op_sel_hi:[1,0]
	v_pk_add_f32 v[124:125], v[124:125], 1.0 op_sel_hi:[1,0]
	v_cvt_pk_bf16_f32 v30, v30, v31
	v_cvt_pk_bf16_f32 v31, v32, v33
	global_store_dwordx2 v[36:37], v[30:31], off
	v_pk_fma_f32 v[28:29], v[122:123], v[28:29], v[106:107]
	v_pk_fma_f32 v[26:27], v[120:121], v[26:27], v[104:105]
	v_pk_add_f32 v[130:131], v[130:131], 1.0 op_sel_hi:[1,0]
	v_pk_add_f32 v[128:129], v[128:129], 1.0 op_sel_hi:[1,0]
	v_cvt_pk_bf16_f32 v26, v26, v27
	v_cvt_pk_bf16_f32 v27, v28, v29
	global_store_dwordx2 v[36:37], v[26:27], off offset:512
	v_pk_fma_f32 v[24:25], v[126:127], v[24:25], v[110:111]
	v_pk_fma_f32 v[22:23], v[124:125], v[22:23], v[108:109]
	s_nop 0
	v_cvt_pk_bf16_f32 v22, v22, v23
	v_cvt_pk_bf16_f32 v23, v24, v25
	global_store_dwordx2 v[36:37], v[22:23], off offset:1024
	v_pk_fma_f32 v[20:21], v[130:131], v[20:21], v[114:115]
	v_pk_fma_f32 v[18:19], v[128:129], v[18:19], v[112:113]
	s_nop 0
	v_cvt_pk_bf16_f32 v18, v18, v19
	v_cvt_pk_bf16_f32 v19, v20, v21
	global_store_dwordx2 v[36:37], v[18:19], off offset:1536
	v_lshl_add_u64 v[36:37], v[36:37], 0, s[56:57]
	s_cbranch_scc0 .LBB0_784
.LBB0_778:
	s_min_i32 s98, s24, 0x8000
	s_ashr_i32 s98, s98, 11
	s_mul_hi_i32 s99, s98, 0x9000
	s_mul_i32 s98, s98, 0x9000
	s_add_u32 s98, s28, s98
	s_addc_u32 s99, s29, s99
	s_add_u32 s100, s98, 0x1000
	s_addc_u32 s101, s99, 0
	v_lshlrev_b32_e32 v132, 2, v34
	global_load_dwordx4 v[100:103], v132, s[98:99]
	global_load_dwordx4 v[104:107], v132, s[98:99] offset:1024
	global_load_dwordx4 v[108:111], v132, s[98:99] offset:2048
	global_load_dwordx4 v[112:115], v132, s[98:99] offset:3072
	global_load_dwordx4 v[116:119], v132, s[100:101]
	global_load_dwordx4 v[120:123], v132, s[100:101] offset:1024
	global_load_dwordx4 v[124:127], v132, s[100:101] offset:2048
	global_load_dwordx4 v[128:131], v132, s[100:101] offset:3072
	s_add_i32 s9, s24, 0xffff8000
	s_cmpk_gt_i32 s24, 0x7fff
	s_cselect_b64 s[2:3], -1, 0
	s_and_b64 s[4:5], s[2:3], exec
	s_cselect_b32 s26, s9, s24
	s_cselect_b32 s5, s23, s13
	s_cselect_b32 s4, s22, s12
	s_ashr_i32 s27, s26, 31
	s_lshl_b64 s[26:27], s[26:27], 10
	v_mov_b32_e32 v39, s27
	v_or_b32_e32 v38, s26, v34
	s_mov_b64 s[26:27], -1
	s_and_b64 vcc, exec, s[72:73]
	s_cbranch_vccz .LBB0_781
	s_waitcnt vmcnt(12)
	v_cvt_f32_f16_e32 v30, v72
	v_cvt_f32_f16_sdwa v31, v72 dst_sel:DWORD dst_unused:UNUSED_PAD src0_sel:WORD_1
	v_cvt_f32_f16_e32 v32, v73
	v_cvt_f32_f16_sdwa v33, v73 dst_sel:DWORD dst_unused:UNUSED_PAD src0_sel:WORD_1
	v_cvt_f32_f16_e32 v26, v74
	v_cvt_f32_f16_sdwa v27, v74 dst_sel:DWORD dst_unused:UNUSED_PAD src0_sel:WORD_1
	v_cvt_f32_f16_e32 v28, v75
	v_cvt_f32_f16_sdwa v29, v75 dst_sel:DWORD dst_unused:UNUSED_PAD src0_sel:WORD_1
	v_cvt_f32_f16_e32 v22, v76
	v_cvt_f32_f16_sdwa v23, v76 dst_sel:DWORD dst_unused:UNUSED_PAD src0_sel:WORD_1
	v_cvt_f32_f16_e32 v24, v77
	v_cvt_f32_f16_sdwa v25, v77 dst_sel:DWORD dst_unused:UNUSED_PAD src0_sel:WORD_1
	v_cvt_f32_f16_e32 v18, v78
	v_cvt_f32_f16_sdwa v19, v78 dst_sel:DWORD dst_unused:UNUSED_PAD src0_sel:WORD_1
	v_cvt_f32_f16_e32 v20, v79
	v_cvt_f32_f16_sdwa v21, v79 dst_sel:DWORD dst_unused:UNUSED_PAD src0_sel:WORD_1
	s_add_i32 s98, s24, s10
	s_cmp_lt_i32 s98, s20
	s_cselect_b32 s98, s98, s24
	s_add_i32 s99, s98, 0xffff8000
	s_cmpk_gt_i32 s98, 0x7fff
	s_cselect_b32 s98, s99, s98
	s_cselect_b32 s101, s23, s13
	s_cselect_b32 s100, s22, s12
	s_ashr_i32 s99, s98, 31
	s_lshl_b64 s[98:99], s[98:99], 10
	v_mov_b32_e32 v81, s99
	v_or_b32_e32 v80, s98, v34
	v_lshl_add_u64 v[80:81], v[80:81], 1, s[100:101]
	global_load_dwordx2 v[72:73], v[80:81], off
	global_load_dwordx2 v[74:75], v[80:81], off offset:512
	global_load_dwordx2 v[76:77], v[80:81], off offset:1024
	global_load_dwordx2 v[78:79], v[80:81], off offset:1536
	s_cbranch_execz .LBB0_782

.Lnf_head16:
	v_pk_mul_f32 v[42:43], v[32:33], v[32:33]
	v_pk_mul_f32 v[44:45], v[30:31], v[30:31]
	v_pk_mul_f32 v[38:39], v[28:29], v[28:29]
	v_pk_mul_f32 v[40:41], v[26:27], v[26:27]
	v_pk_mov_b32 v[46:47], v[44:45], v[42:43] op_sel:[1,0]
	v_mov_b32_e32 v45, v43
	v_pk_add_f32 v[42:43], v[46:47], v[44:45]
	v_pk_mov_b32 v[44:45], v[40:41], v[38:39] op_sel:[1,0]
	v_mov_b32_e32 v41, v39
	v_mul_f32_e32 v0, v22, v22
	v_pk_add_f32 v[38:39], v[44:45], v[40:41]
	v_pk_fma_f32 v[40:41], v[22:23], v[22:23], v[0:1] op_sel_hi:[1,1,0]
	v_mul_f32_e32 v0, v24, v24
	v_pk_add_f32 v[42:43], v[42:43], v[42:43] op_sel_hi:[0,1]
	v_pk_add_f32 v[38:39], v[38:39], v[38:39] op_sel_hi:[0,1]
	v_pk_fma_f32 v[44:45], v[24:25], v[24:25], v[0:1] op_sel_hi:[1,1,0]
	s_branch .Lnf_join
